# w_in_a of the second layer pair also transposed in layer 0's in-projection slot (P0 keeps only w_in_a[0])
# baseline (speedup 1.0000x reference)
; DI void phase_p0(const Params& p, LAS unsigned char* lds, int gw, int NGW, int wave, int lane) {
;     ...
;     constexpr int I_INA = (D / 128) * (NA / 32), I_OUT = (D / 128) * (D / 32), I_INB = (D / 128) * (NB / 32);
;     constexpr int NITEMS = 2 * (I_INA + I_OUT + I_INB + I_OUT);
;     for (int it = gw; it < NITEMS; it += NGW) {
; __global__ void __launch_bounds__(NTHREADS) hybrid_fwd(Params p) {
;     ...
;         const int tid = threadIdx.x, lane = tid & 63, wave = __builtin_amdgcn_readfirstlane(tid >> 6);
;         const int G = gridDim.x, gw = blockIdx.x * NWAVES + wave, NGW = G * NWAVES;
;         if (tid < 2) bst[tid] = 0u;
;         if (blockIdx.x == 0) { for (int i = tid; i < XCD_BAR_WORDS; i += NTHREADS) barw[i] = 0u; for (int i = tid; i < 4 * 8 * 64; i += NTHREADS) ((unsigned*)(p.ws + WS_Q))[i] = 0u; }
_Z10hybrid_fwd6Params:
	s_mov_b32 s100, 0
	s_movk_i32 s101, 0x8ff
	v_writelane_b32 v245, s0, 0
	v_writelane_b32 v245, s1, 1
	s_load_dwordx8 s[88:95], s[0:1], 0x40
	s_load_dword s99, s[0:1], 0x68
	s_add_u32 s6, s0, 0x68
	v_and_b32_e32 v34, 0x3ff, v0
	s_addc_u32 s7, s1, 0
	v_readfirstlane_b32 s16, v34
	v_cmp_gt_u32_e32 vcc, 2, v34
	s_and_saveexec_b64 s[8:9], vcc
	v_lshl_add_u32 v1, v34, 2, 0
	v_add_u32_e32 v1, 0x24000, v1
	v_mov_b32_e32 v2, 0
	ds_write_b32 v1, v2
	s_or_b64 exec, exec, s[8:9]
	s_waitcnt lgkmcnt(0)
	s_add_u32 s96, s94, 0x1c900000
	s_addc_u32 s97, s95, 0
	s_cmp_lg_u32 s2, 0
	s_mov_b32 s8, 0
	s_cbranch_scc1 .LBB0_14
	v_sub_u32_e32 v1, 0xd7f, v34
	v_lshrrev_b32_e32 v4, 9, v1
	v_add_u32_e32 v1, 2, v4
	v_add_u32_e32 v3, 0x200, v34
	v_mov_b32_e32 v2, v34
	v_and_b32_e32 v10, 14, v1
	v_mov_b32_e32 v5, v4
	v_mov_b32_e32 v1, v34
	s_mov_b64 s[10:11], 0
	s_mov_b32 s9, 1
	v_mov_b32_e32 v7, 0
	s_mov_b32 s12, s8
	v_mov_b64_e32 v[8:9], v[2:3]
	s_branch .LBB0_5

; DI void phase_p0(const Params& p, LAS unsigned char* lds, int gw, int NGW, int wave, int lane) {
;     ...
;     constexpr int I_INA = (D / 128) * (NA / 32), I_OUT = (D / 128) * (D / 32), I_INB = (D / 128) * (NB / 32);
;     constexpr int NITEMS = 2 * (I_INA + I_OUT + I_INB + I_OUT);
;     for (int it = gw; it < NITEMS; it += NGW) {
;         int r = it;
;         if (r < 2 * I_INA) { const int j = r / I_INA; p0_transpose_item(p.w_in_a + (size_t)j * D * NA, D, NA, (bf16_t*)(p.ws + WS_W + j * WPAIR + WO_INA), scr, r % I_INA, lane); continue; } r -= 2 * I_INA;
; __global__ void __launch_bounds__(NTHREADS) hybrid_fwd(Params p) {
;     ...
;         const int G = gridDim.x, gw = blockIdx.x * NWAVES + wave, NGW = G * NWAVES;
.LBB0_14:
	s_load_dwordx16 s[72:87], s[0:1], 0x0
	s_lshr_b32 s1, s16, 6
	s_lshl_b32 s0, s2, 3
	s_add_i32 s4, s1, s0
	s_lshl_b32 s0, s99, 3
	s_cmpk_gt_i32 s4, 0x8ff
	v_and_b32_e32 v1, 63, v34
	v_writelane_b32 v239, s2, 0
	s_cbranch_scc1 .LBB0_29

; DI void phase_p0(const Params& p, LAS unsigned char* lds, int gw, int NGW, int wave, int lane) {
;     ...
;     bf16_t* hb = (bf16_t*)(p.ws + WS_HB);
;     { unsigned char* zb = p.ws + WS_Z;
;       for (size_t i = (size_t)(gw * 64 + lane) * 16; i < (size_t)(18 + 32) << 17; i += (size_t)NGW * 64 * 16) {
;           unsigned char* dst = i < ((size_t)18 << 17) ? zb + ((size_t)(64 * 18) << 17) + i : zb + ((size_t)(64 * 32) << 17) + (i - ((size_t)18 << 17));
;           *(u32x4*)dst = (u32x4){0u, 0u, 0u, 0u}; } }
.LBB0_29:
	s_cmpk_lg_i32 s101, 0x8ff
	s_cbranch_scc1 .Lslot_ret
	v_lshl_or_b32 v2, s4, 6, v1
	v_ashrrev_i32_e32 v3, 31, v2
	v_lshlrev_b64 v[2:3], 4, v[2:3]
	s_mov_b64 s[8:9], 0x640000
	v_cmp_gt_u64_e32 vcc, s[8:9], v[2:3]
	s_and_saveexec_b64 s[8:9], vcc
	s_cbranch_execz .LBB0_32
	s_ashr_i32 s1, s0, 31
	v_mov_b32_e32 v5, 0
	s_lshl_b64 s[10:11], s[0:1], 10
	s_mov_b64 s[12:13], 0
	s_mov_b64 s[14:15], 0x240000
	v_mov_b32_e32 v6, 0x1c2c0000
	v_mov_b32_e32 v7, 0x15500000
	v_mov_b32_e32 v8, v5
	v_mov_b32_e32 v9, v5
	v_mov_b32_e32 v10, v5
	v_mov_b32_e32 v11, v5
	s_mov_b64 s[16:17], 0x63ffff

; DI void phase_p0(const Params& p, LAS unsigned char* lds, int gw, int NGW, int wave, int lane) {
;     ...
;         if (r < 2 * I_INA) { const int j = r / I_INA; p0_transpose_item(p.w_in_a + (size_t)j * D * NA, D, NA, (bf16_t*)(p.ws + WS_W + j * WPAIR + WO_INA), scr, r % I_INA, lane); continue; } r -= 2 * I_INA;
;         if (r < 2 * I_OUT) { const int j = r / I_OUT; p0_transpose_item(p.w_out_a + (size_t)j * D * D, D, D, (bf16_t*)(p.ws + WS_W + j * WPAIR + WO_OUTA), scr, r % I_OUT, lane); continue; } r -= 2 * I_OUT;
;         if (r < 2 * I_INB) { const int j = r / I_INB; p0_transpose_item(p.w_in_b + (size_t)j * D * NB, D, NB, (bf16_t*)(p.ws + WS_W + j * WPAIR + WO_INB), scr, r % I_INB, lane); continue; } r -= 2 * I_INB;
;         { const int j = r / I_OUT; p0_transpose_item(p.w_out_b + (size_t)j * D * D, D, D, (bf16_t*)(p.ws + WS_W + j * WPAIR + WO_OUTB), scr, r % I_OUT, lane); }
.Lslot_next:
	s_cmp_eq_u32 s88, 4
	s_cbranch_scc1 .Lslot_done
	s_lshl_b32 s4, s90, 10
	s_addk_i32 s4, 0x1200
	s_add_i32 s101, s4, 0x3ff
	s_cmp_eq_u32 s88, 1
	s_cbranch_scc0 .Lslot_r2
	s_lshl_b32 s4, s90, 12
	s_addk_i32 s4, 0x1a00
	s_add_i32 s101, s4, 0xfff

; DI void phase_p0(const Params& p, LAS unsigned char* lds, int gw, int NGW, int wave, int lane) {
;     ...
;         if (r < 2 * I_INA) { const int j = r / I_INA; p0_transpose_item(p.w_in_a + (size_t)j * D * NA, D, NA, (bf16_t*)(p.ws + WS_W + j * WPAIR + WO_INA), scr, r % I_INA, lane); continue; } r -= 2 * I_INA;
.Lslot_r3:
	s_cmp_eq_u32 s88, 3
	s_cbranch_scc0 .Lslot_go
	s_cmp_lg_u32 s90, 0
	s_cbranch_scc1 .Lslot_done
	s_movk_i32 s4, 0x900
	s_movk_i32 s101, 0x11ff
